# diff_final loop: two items per trip, six loads in flight per wave (suffix vmcnt waits)
# baseline (speedup 1.0000x reference)
; __device__ __forceinline__ unsigned pk2(float lo, float hi) { return pg8::cvt_pk_bf16(lo, hi); }
; __device__ __forceinline__ void diff_final(const bfu* D0, const bfu* D1, float lam, const float* sg, float omli, bfu* CAT, int gw, int NGW, int lane) {
;     ...
;     for (int it = gw * 2 + half; it < M * 6; it += NGW * 2) { const int row = it / 6, h = it - row * 6;
;         const v2u a_ = __builtin_nontemporal_load((const v2u*)(D0 + (size_t)row * 768 + h * 128 + l32 * 4)), b_ = __builtin_nontemporal_load((const v2u*)(D1 + (size_t)row * 768 + h * 128 + l32 * 4));
;         const f32x4 v = (f32x4){bflo(a_.x), bfhi(a_.x), bflo(a_.y), bfhi(a_.y)} - (f32x4){bflo(b_.x), bfhi(b_.x), bflo(b_.y), bfhi(b_.y)} * lam; float s = (v.x * v.x + v.y * v.y) + (v.z * v.z + v.w * v.w);
; #pragma unroll
;         for (int o = 1; o < 32; o <<= 1) s += __shfl_xor(s, o);
;         const float r = omli / sqrtf(s * (1.f / 128.f) + EPS); const f32x4 g4 = *(const f32x4*)(sg + h * 128 + l32 * 4);
;         v2u w; w.x = pk2(v.x * r * g4.x, v.y * r * g4.y); w.y = pk2(v.z * r * g4.z, v.w * r * g4.w); *(v2u*)(CAT + (size_t)row * DM + 768 + h * 128 + l32 * 4) = w; }
.LBB0_501:
	s_mov_b32 s22, 0x2aaaaaab
	v_mul_hi_i32 v16, v10, s22
	v_lshrrev_b32_e32 v17, 31, v16
	v_mov_b64_e32 v[12:13], s[40:41]
	v_add_u32_e32 v16, v16, v17
	v_mad_i64_i32 v[12:13], s[22:23], v16, s66, v[12:13]
	s_movk_i32 s22, 0xfd00
	s_nop 0
	v_mad_u64_u32 v[18:19], s[22:23], v16, s22, v[4:5]
	v_ashrrev_i32_e32 v19, 31, v18
	v_mov_b64_e32 v[14:15], s[44:45]
	v_lshlrev_b64 v[20:21], 1, v[18:19]
	v_mad_i64_i32 v[14:15], s[22:23], v16, s66, v[14:15]
	v_lshl_add_u64 v[12:13], v[12:13], 0, v[20:21]
	v_lshl_add_u64 v[14:15], v[14:15], 0, v[20:21]
	v_lshl_add_u64 v[12:13], v[12:13], 0, v[0:1]
	v_lshl_add_u64 v[14:15], v[14:15], 0, v[0:1]
	global_load_dwordx2 v[22:23], v[12:13], off nt
	global_load_dwordx2 v[24:25], v[14:15], off nt
	v_ashrrev_i32_e32 v17, 31, v16
	v_lshlrev_b64 v[12:13], 12, v[16:17]
	v_lshl_add_u64 v[14:15], v[18:19], 2, v[2:3]
	v_lshl_add_u64 v[16:17], s[34:35], 0, v[12:13]
	global_load_dwordx4 v[12:15], v[14:15], off
	s_xor_b32 s47, s20, 0x80000000
	v_lshl_add_u64 v[16:17], v[16:17], 0, v[20:21]
	v_add_u32_e32 v10, 0x40, v10
	s_and_b32 s22, s2, 7
	s_lshl_b32 s22, s22, 3
	s_bfe_u32 s23, s2, 0x30003
	s_add_i32 s22, s22, s23
	s_mulk_i32 s22, 0x600
	s_addk_i32 s22, 0x5ff
	v_cmp_lt_i32_e32 vcc, s22, v10
	s_or_b64 s[36:37], vcc, s[36:37]
	v_lshl_add_u64 v[16:17], v[16:17], 0, v[0:1]
	v_add_u32_e32 v4, 0x2000, v4
	s_mov_b32 s22, 0x2aaaaaab
	v_mul_hi_i32 v48, v10, s22
	v_lshrrev_b32_e32 v49, 31, v48
	v_mov_b64_e32 v[44:45], s[40:41]
	v_add_u32_e32 v48, v48, v49
	v_mad_i64_i32 v[44:45], s[22:23], v48, s66, v[44:45]
	s_movk_i32 s22, 0xfd00
	s_nop 0
	v_mad_u64_u32 v[50:51], s[22:23], v48, s22, v[4:5]
	v_ashrrev_i32_e32 v51, 31, v50
	v_mov_b64_e32 v[46:47], s[44:45]
	v_lshlrev_b64 v[52:53], 1, v[50:51]
	v_mad_i64_i32 v[46:47], s[22:23], v48, s66, v[46:47]
	v_lshl_add_u64 v[44:45], v[44:45], 0, v[52:53]
	v_lshl_add_u64 v[46:47], v[46:47], 0, v[52:53]
	v_lshl_add_u64 v[44:45], v[44:45], 0, v[0:1]
	v_lshl_add_u64 v[46:47], v[46:47], 0, v[0:1]
	global_load_dwordx2 v[54:55], v[44:45], off nt
	global_load_dwordx2 v[56:57], v[46:47], off nt
	v_ashrrev_i32_e32 v49, 31, v48
	v_lshlrev_b64 v[44:45], 12, v[48:49]
	v_lshl_add_u64 v[46:47], v[50:51], 2, v[2:3]
	v_lshl_add_u64 v[48:49], s[34:35], 0, v[44:45]
	global_load_dwordx4 v[44:47], v[46:47], off
	s_xor_b32 s47, s20, 0x80000000
	v_lshl_add_u64 v[48:49], v[48:49], 0, v[52:53]
	v_add_u32_e32 v10, 0x40, v10
	s_and_b32 s22, s2, 7
	s_lshl_b32 s22, s22, 3
	s_bfe_u32 s23, s2, 0x30003
	s_add_i32 s22, s22, s23
	s_mulk_i32 s22, 0x600
	s_addk_i32 s22, 0x5ff
	v_cmp_lt_i32_e32 vcc, s22, v10
	s_or_b64 s[36:37], vcc, s[36:37]
	v_lshl_add_u64 v[48:49], v[48:49], 0, v[0:1]
	v_add_u32_e32 v4, 0x2000, v4
	s_waitcnt vmcnt(5)
	v_lshlrev_b32_e32 v18, 16, v22
	v_and_b32_e32 v19, 0xffff0000, v22
	v_lshlrev_b32_e32 v20, 16, v23
	v_and_b32_e32 v21, 0xffff0000, v23
	s_waitcnt vmcnt(4)
	v_lshlrev_b32_e32 v22, 16, v24
	v_and_b32_e32 v23, 0xffff0000, v24
	v_lshlrev_b32_e32 v24, 16, v25
	v_and_b32_e32 v25, 0xffff0000, v25
	v_pk_fma_f32 v[18:19], s[26:27], v[22:23], v[18:19] neg_lo:[1,0,0] neg_hi:[1,0,0]
	v_pk_fma_f32 v[20:21], s[46:47], v[24:25], v[20:21]
	v_pk_mul_f32 v[24:25], v[18:19], v[18:19]
	v_pk_mul_f32 v[22:23], v[20:21], v[20:21]
	s_nop 0
	v_pk_mov_b32 v[26:27], v[24:25], v[22:23] op_sel:[1,0]
	v_mov_b32_e32 v25, v23
	v_pk_add_f32 v[22:23], v[26:27], v[24:25]
	s_nop 0
	v_add_f32_e32 v22, v22, v23
	s_waitcnt lgkmcnt(0)
; __device__ __forceinline__ unsigned pk2(float lo, float hi) { return pg8::cvt_pk_bf16(lo, hi); }
; __device__ __forceinline__ void diff_final(const bfu* D0, const bfu* D1, float lam, const float* sg, float omli, bfu* CAT, int gw, int NGW, int lane) {
;     ...
;     for (int it = gw * 2 + half; it < M * 6; it += NGW * 2) { const int row = it / 6, h = it - row * 6;
;         const v2u a_ = __builtin_nontemporal_load((const v2u*)(D0 + (size_t)row * 768 + h * 128 + l32 * 4)), b_ = __builtin_nontemporal_load((const v2u*)(D1 + (size_t)row * 768 + h * 128 + l32 * 4));
;         const f32x4 v = (f32x4){bflo(a_.x), bfhi(a_.x), bflo(a_.y), bfhi(a_.y)} - (f32x4){bflo(b_.x), bfhi(b_.x), bflo(b_.y), bfhi(b_.y)} * lam; float s = (v.x * v.x + v.y * v.y) + (v.z * v.z + v.w * v.w);
; #pragma unroll
;         for (int o = 1; o < 32; o <<= 1) s += __shfl_xor(s, o);
;         const float r = omli / sqrtf(s * (1.f / 128.f) + EPS); const f32x4 g4 = *(const f32x4*)(sg + h * 128 + l32 * 4);
;         v2u w; w.x = pk2(v.x * r * g4.x, v.y * r * g4.y); w.y = pk2(v.z * r * g4.z, v.w * r * g4.w); *(v2u*)(CAT + (size_t)row * DM + 768 + h * 128 + l32 * 4) = w; }
	s_nop 1
	v_add_f32_dpp v22, v22, v22 quad_perm:[1,0,3,2] row_mask:0xf bank_mask:0xf
	s_nop 1
	v_add_f32_dpp v22, v22, v22 quad_perm:[2,3,0,1] row_mask:0xf bank_mask:0xf
	s_nop 1
	v_add_f32_dpp v22, v22, v22 row_half_mirror row_mask:0xf bank_mask:0xf
	s_nop 1
	v_add_f32_dpp v22, v22, v22 row_mirror row_mask:0xf bank_mask:0xf
	v_mov_b32_e32 v23, v22
	s_nop 1
	v_permlane16_swap_b32_e32 v22, v23
	v_add_f32_e32 v22, v22, v23
	v_fmamk_f32 v22, v22, 0x3c000000, v236
	v_mul_f32_e32 v23, 0x4f800000, v22
	v_cmp_gt_f32_e32 vcc, s68, v22
	s_nop 1
	v_cndmask_b32_e32 v22, v22, v23, vcc
	v_sqrt_f32_e32 v23, v22
	s_nop 0
	v_add_u32_e32 v24, -1, v23
	v_add_u32_e32 v25, 1, v23
	v_fma_f32 v26, -v24, v23, v22
	v_fma_f32 v27, -v25, v23, v22
	v_cmp_ge_f32_e64 s[38:39], 0, v26
	s_nop 1
	v_cndmask_b32_e64 v23, v23, v24, s[38:39]
	v_cmp_lt_f32_e64 s[38:39], 0, v27
	s_nop 1
	v_cndmask_b32_e64 v23, v23, v25, s[38:39]
	v_mul_f32_e32 v24, 0x37800000, v23
	v_cndmask_b32_e32 v23, v23, v24, vcc
	v_cmp_class_f32_e32 vcc, v22, v234
	s_nop 1
	v_cndmask_b32_e32 v22, v23, v22, vcc
	v_div_scale_f32 v23, s[22:23], v22, v22, v11
	v_rcp_f32_e32 v25, v23
	v_div_scale_f32 v24, vcc, v11, v22, v11
	v_fma_f32 v26, -v23, v25, 1.0
	v_fmac_f32_e32 v25, v26, v25
	v_mul_f32_e32 v26, v24, v25
	v_fma_f32 v27, -v23, v26, v24
	v_fmac_f32_e32 v26, v27, v25
	v_fma_f32 v23, -v23, v26, v24
	v_div_fmas_f32 v23, v23, v25, v26
	v_div_fixup_f32 v22, v23, v22, v11
	v_pk_mul_f32 v[18:19], v[18:19], v[22:23] op_sel_hi:[1,0]
	v_pk_mul_f32 v[20:21], v[20:21], v[22:23] op_sel_hi:[1,0]
	v_add_co_u32_e32 v16, vcc, 0x29600000, v16
	s_waitcnt vmcnt(3)
	v_pk_mul_f32 v[12:13], v[12:13], v[18:19]
	v_pk_mul_f32 v[14:15], v[14:15], v[20:21]
	v_addc_co_u32_e32 v17, vcc, 0, v17, vcc
	v_cvt_pk_bf16_f32 v12, v12, v13
	v_cvt_pk_bf16_f32 v13, v14, v15
	global_store_dwordx2 v[16:17], v[12:13], off offset:1536
	s_waitcnt vmcnt(2)
	v_lshlrev_b32_e32 v50, 16, v54
	v_and_b32_e32 v51, 0xffff0000, v54
	v_lshlrev_b32_e32 v52, 16, v55
	v_and_b32_e32 v53, 0xffff0000, v55
	s_waitcnt vmcnt(1)
	v_lshlrev_b32_e32 v54, 16, v56
	v_and_b32_e32 v55, 0xffff0000, v56
	v_lshlrev_b32_e32 v56, 16, v57
	v_and_b32_e32 v57, 0xffff0000, v57
	v_pk_fma_f32 v[50:51], s[26:27], v[54:55], v[50:51] neg_lo:[1,0,0] neg_hi:[1,0,0]
	v_pk_fma_f32 v[52:53], s[46:47], v[56:57], v[52:53]
	v_pk_mul_f32 v[56:57], v[50:51], v[50:51]
	v_pk_mul_f32 v[54:55], v[52:53], v[52:53]
	s_nop 0
	v_pk_mov_b32 v[58:59], v[56:57], v[54:55] op_sel:[1,0]
	v_mov_b32_e32 v57, v55
	v_pk_add_f32 v[54:55], v[58:59], v[56:57]
	s_nop 0
	v_add_f32_e32 v54, v54, v55
	s_waitcnt lgkmcnt(0)
	s_nop 1
	v_add_f32_dpp v54, v54, v54 quad_perm:[1,0,3,2] row_mask:0xf bank_mask:0xf
	s_nop 1
	v_add_f32_dpp v54, v54, v54 quad_perm:[2,3,0,1] row_mask:0xf bank_mask:0xf
	s_nop 1
	v_add_f32_dpp v54, v54, v54 row_half_mirror row_mask:0xf bank_mask:0xf
	s_nop 1
	v_add_f32_dpp v54, v54, v54 row_mirror row_mask:0xf bank_mask:0xf
	v_mov_b32_e32 v55, v54
	s_nop 1
	v_permlane16_swap_b32_e32 v54, v55
	v_add_f32_e32 v54, v54, v55
	v_fmamk_f32 v54, v54, 0x3c000000, v236
	v_mul_f32_e32 v55, 0x4f800000, v54
	v_cmp_gt_f32_e32 vcc, s68, v54
	s_nop 1
	v_cndmask_b32_e32 v54, v54, v55, vcc
	v_sqrt_f32_e32 v55, v54
	s_nop 0
	v_add_u32_e32 v56, -1, v55
	v_add_u32_e32 v57, 1, v55
	v_fma_f32 v58, -v56, v55, v54
	v_fma_f32 v59, -v57, v55, v54
	v_cmp_ge_f32_e64 s[38:39], 0, v58
	s_nop 1
	v_cndmask_b32_e64 v55, v55, v56, s[38:39]
	v_cmp_lt_f32_e64 s[38:39], 0, v59
	s_nop 1
	v_cndmask_b32_e64 v55, v55, v57, s[38:39]
	v_mul_f32_e32 v56, 0x37800000, v55
	v_cndmask_b32_e32 v55, v55, v56, vcc
	v_cmp_class_f32_e32 vcc, v54, v234
	s_nop 1
	v_cndmask_b32_e32 v54, v55, v54, vcc
	v_div_scale_f32 v55, s[22:23], v54, v54, v11
	v_rcp_f32_e32 v57, v55
	v_div_scale_f32 v56, vcc, v11, v54, v11
	v_fma_f32 v58, -v55, v57, 1.0
	v_fmac_f32_e32 v57, v58, v57
	v_mul_f32_e32 v58, v56, v57
	v_fma_f32 v59, -v55, v58, v56
	v_fmac_f32_e32 v58, v59, v57
	v_fma_f32 v55, -v55, v58, v56
	v_div_fmas_f32 v55, v55, v57, v58
	v_div_fixup_f32 v54, v55, v54, v11
	v_pk_mul_f32 v[50:51], v[50:51], v[54:55] op_sel_hi:[1,0]
	v_pk_mul_f32 v[52:53], v[52:53], v[54:55] op_sel_hi:[1,0]
	v_add_co_u32_e32 v48, vcc, 0x29600000, v48
	s_waitcnt vmcnt(0)
	v_pk_mul_f32 v[44:45], v[44:45], v[50:51]
	v_pk_mul_f32 v[46:47], v[46:47], v[52:53]
	v_addc_co_u32_e32 v49, vcc, 0, v49, vcc
	v_cvt_pk_bf16_f32 v44, v44, v45
	v_cvt_pk_bf16_f32 v45, v46, v47
	global_store_dwordx2 v[48:49], v[44:45], off offset:1536
	s_andn2_b64 exec, exec, s[36:37]
	s_cbranch_execnz .LBB0_501
